# L1/L2 out-proj residual preload loads non-temporal
# baseline (speedup 1.0000x reference)
; __device__ __forceinline__ float bflo(unsigned u) { return __uint_as_float(u << 16); }
; __device__ __forceinline__ float bfhi(unsigned u) { return __uint_as_float(u & 0xffff0000u); }
; template <class Epi, class Sched, bool ALIGN_EPI = false, bool SP2 = false>
; __device__ __forceinline__ void gemm_phase(PG8_LAS unsigned char* lds, const Gemm g, const Sched& S, const Epi& E) {
;     ...
; #pragma unroll
;         for (int a = 0; a < 2; ++a)
; #pragma unroll
;             for (int b = 0; b < 2; ++b)
; #pragma unroll
;                 for (int m = 0; m < 4; ++m)
; #pragma unroll
;                     for (int n = 0; n < 2; ++n) acc[a][b][m][n] = (f32x4){0.f, 0.f, 0.f, 0.f};
;         cur = nxt; cA = nA; cB = nB; ++ui;
;     __device__ __forceinline__ void operator()(const f32x4 (&acc)[2][2][4][2], const pg8::Unit& u, int wr, int wc, int fr, int fq) const {
;     ...
;                     const size_t off = (size_t)row * 1024 + c0 + bj * 128;
;                     f32x4 x0, x1;
;                     if (xin) { x0 = *(const f32x4*)(xin + off); x1 = *(const f32x4*)(xin + off + 4); }
;                     else { const v4u xv = *(const v4u*)(xb + off); x0 = (f32x4){bflo(xv.x), bfhi(xv.x), bflo(xv.y), bfhi(xv.y)}; x1 = (f32x4){bflo(xv.z), bfhi(xv.z), bflo(xv.w), bfhi(xv.w)}; }
.LBB0_463:
	s_ashr_i32 s13, s12, 31
	s_lshl_b64 s[14:15], s[12:13], 19
	s_add_u32 s14, s50, s14
	s_addc_u32 s15, s51, s15
	s_and_b64 s[18:19], s[4:5], exec
	s_cselect_b32 s13, s15, s3
	s_cselect_b32 s39, s14, s2
	s_ashr_i32 s11, s10, 31
	s_lshl_b64 s[18:19], s[10:11], 19
	v_readlane_b32 s22, v254, 3
	v_readlane_b32 s23, v254, 4
	s_add_u32 s18, s22, s18
	s_addc_u32 s19, s23, s19
	s_and_b64 s[22:23], s[4:5], exec
	s_cselect_b32 s11, s19, s21
	s_cselect_b32 s42, s18, s20
	s_add_u32 s2, s2, 0x40080
	s_addc_u32 s3, s3, 0
	s_add_u32 s43, s20, 0x100
	v_mov_b32_e32 v2, 0
	s_addc_u32 s44, s21, 0
	s_mov_b32 s45, -2
	s_waitcnt lgkmcnt(0)
	v_mov_b32_e32 v3, v2
	v_mov_b32_e32 v4, v2
	v_mov_b32_e32 v5, v2
	v_mov_b32_e32 v6, v2
	v_mov_b32_e32 v7, v2
	v_mov_b32_e32 v8, v2
	v_mov_b32_e32 v9, v2
	v_mov_b32_e32 v18, v2
	v_mov_b32_e32 v19, v2
	v_mov_b32_e32 v20, v2
	v_mov_b32_e32 v21, v2
	v_mov_b32_e32 v22, v2
	v_mov_b32_e32 v23, v2
	v_mov_b32_e32 v24, v2
	v_mov_b32_e32 v25, v2
	v_mov_b32_e32 v34, v2
	v_mov_b32_e32 v35, v2
	v_mov_b32_e32 v36, v2
	v_mov_b32_e32 v37, v2
	v_mov_b32_e32 v38, v2
	v_mov_b32_e32 v39, v2
	v_mov_b32_e32 v40, v2
	v_mov_b32_e32 v41, v2
	s_waitcnt vmcnt(0)
	v_mov_b32_e32 v50, v2
	v_mov_b32_e32 v51, v2
	v_mov_b32_e32 v52, v2
	v_mov_b32_e32 v53, v2
	v_mov_b32_e32 v54, v2
	v_mov_b32_e32 v55, v2
	v_mov_b32_e32 v56, v2
	v_mov_b32_e32 v57, v2
	v_mov_b32_e32 v10, v2
	v_mov_b32_e32 v11, v2
	v_mov_b32_e32 v12, v2
	v_mov_b32_e32 v13, v2
	v_mov_b32_e32 v14, v2
	v_mov_b32_e32 v15, v2
	v_mov_b32_e32 v16, v2
	v_mov_b32_e32 v17, v2
	v_mov_b32_e32 v26, v2
	v_mov_b32_e32 v27, v2
	v_mov_b32_e32 v28, v2
	v_mov_b32_e32 v29, v2
	v_mov_b32_e32 v30, v2
	v_mov_b32_e32 v31, v2
	v_mov_b32_e32 v32, v2
	v_mov_b32_e32 v33, v2
	v_mov_b32_e32 v42, v2
	v_mov_b32_e32 v43, v2
	v_mov_b32_e32 v44, v2
	v_mov_b32_e32 v45, v2
	v_mov_b32_e32 v46, v2
	v_mov_b32_e32 v47, v2
	v_mov_b32_e32 v48, v2
	v_mov_b32_e32 v49, v2
	v_mov_b32_e32 v58, v2
	v_mov_b32_e32 v59, v2
	v_mov_b32_e32 v60, v2
	v_mov_b32_e32 v61, v2
	v_mov_b32_e32 v62, v2
	v_mov_b32_e32 v63, v2
	v_mov_b32_e32 v64, v2
	v_mov_b32_e32 v65, v2
	v_mov_b32_e32 v66, v2
	v_mov_b32_e32 v67, v2
	v_mov_b32_e32 v68, v2
	v_mov_b32_e32 v69, v2
	v_mov_b32_e32 v70, v2
	v_mov_b32_e32 v71, v2
	v_mov_b32_e32 v72, v2
	v_mov_b32_e32 v73, v2
	v_mov_b32_e32 v82, v2
	v_mov_b32_e32 v83, v2
	v_mov_b32_e32 v84, v2
	v_mov_b32_e32 v85, v2
	v_mov_b32_e32 v86, v2
	v_mov_b32_e32 v87, v2
	v_mov_b32_e32 v88, v2
	v_mov_b32_e32 v89, v2
	v_mov_b32_e32 v98, v2
	v_mov_b32_e32 v99, v2
	v_mov_b32_e32 v100, v2
	v_mov_b32_e32 v101, v2
	v_mov_b32_e32 v102, v2
	v_mov_b32_e32 v103, v2
	v_mov_b32_e32 v104, v2
	v_mov_b32_e32 v105, v2
	v_mov_b32_e32 v114, v2
	v_mov_b32_e32 v115, v2
	v_mov_b32_e32 v116, v2
	v_mov_b32_e32 v117, v2
	v_mov_b32_e32 v118, v2
	v_mov_b32_e32 v119, v2
	v_mov_b32_e32 v120, v2
	v_mov_b32_e32 v121, v2
	v_mov_b32_e32 v74, v2
	v_mov_b32_e32 v75, v2
	v_mov_b32_e32 v76, v2
	v_mov_b32_e32 v77, v2
	v_mov_b32_e32 v78, v2
	v_mov_b32_e32 v79, v2
	v_mov_b32_e32 v80, v2
	v_mov_b32_e32 v81, v2
	v_mov_b32_e32 v90, v2
	v_mov_b32_e32 v91, v2
	v_mov_b32_e32 v92, v2
	v_mov_b32_e32 v93, v2
	v_mov_b32_e32 v94, v2
	v_mov_b32_e32 v95, v2
	v_mov_b32_e32 v96, v2
	v_mov_b32_e32 v97, v2
	v_mov_b32_e32 v106, v2
	v_mov_b32_e32 v107, v2
	v_mov_b32_e32 v108, v2
	v_mov_b32_e32 v109, v2
	v_mov_b32_e32 v110, v2
	v_mov_b32_e32 v111, v2
	v_mov_b32_e32 v112, v2
	v_mov_b32_e32 v113, v2
	v_mov_b32_e32 v122, v2
	v_mov_b32_e32 v123, v2
	v_mov_b32_e32 v124, v2
	v_mov_b32_e32 v125, v2
	v_mov_b32_e32 v126, v2
	v_mov_b32_e32 v127, v2
	v_mov_b32_e32 v128, v2
	v_mov_b32_e32 v129, v2
	v_readlane_b32 s100, v255, 22
	v_readlane_b32 s101, v255, 23
	v_lshl_add_u32 v196, s38, 8, v1
	v_lshl_or_b32 v198, s37, 8, v170
	v_ashrrev_i32_e32 v197, 31, v196
	v_ashrrev_i32_e32 v199, 31, v198
	v_lshlrev_b64 v[200:201], 10, v[196:197]
	v_lshl_add_u64 v[200:201], v[200:201], 0, v[198:199]
	v_lshl_add_u64 v[200:201], v[200:201], 1, s[100:101]
	v_mov_b32_e32 v217, 0
	v_mov_b32_e32 v216, 0x8000
	v_lshl_add_u64 v[202:203], v[200:201], 0, v[216:217]
	v_mov_b32_e32 v216, 0x10000
	v_lshl_add_u64 v[204:205], v[200:201], 0, v[216:217]
	v_mov_b32_e32 v216, 0x18000
	v_lshl_add_u64 v[206:207], v[200:201], 0, v[216:217]
	v_mov_b32_e32 v216, 0x40000
	v_lshl_add_u64 v[208:209], v[200:201], 0, v[216:217]
	v_mov_b32_e32 v216, 0x48000
	v_lshl_add_u64 v[210:211], v[200:201], 0, v[216:217]
	v_mov_b32_e32 v216, 0x50000
	v_lshl_add_u64 v[212:213], v[200:201], 0, v[216:217]
	v_mov_b32_e32 v216, 0x58000
	v_lshl_add_u64 v[214:215], v[200:201], 0, v[216:217]
	global_load_dwordx4 v[122:125], v[200:201], off nt
	global_load_dwordx4 v[114:117], v[200:201], off offset:256 nt
	global_load_dwordx4 v[106:109], v[202:203], off nt
	global_load_dwordx4 v[98:101], v[202:203], off offset:256 nt
	global_load_dwordx4 v[90:93], v[204:205], off nt
	global_load_dwordx4 v[82:85], v[204:205], off offset:256 nt
	global_load_dwordx4 v[74:77], v[206:207], off nt
	global_load_dwordx4 v[66:69], v[206:207], off offset:256 nt
	global_load_dwordx4 v[58:61], v[208:209], off nt
	global_load_dwordx4 v[50:53], v[208:209], off offset:256 nt
	global_load_dwordx4 v[42:45], v[210:211], off nt
	global_load_dwordx4 v[34:37], v[210:211], off offset:256 nt
	global_load_dwordx4 v[26:29], v[212:213], off nt
	global_load_dwordx4 v[18:21], v[212:213], off offset:256 nt
	global_load_dwordx4 v[10:13], v[214:215], off nt
	global_load_dwordx4 v[2:5], v[214:215], off offset:256 nt
	s_waitcnt vmcnt(0)
; __device__ __forceinline__ float bflo(unsigned u) { return __uint_as_float(u << 16); }
; __device__ __forceinline__ float bfhi(unsigned u) { return __uint_as_float(u & 0xffff0000u); }
;     __device__ __forceinline__ void operator()(const f32x4 (&acc)[2][2][4][2], const pg8::Unit& u, int wr, int wc, int fr, int fq) const {
;     ...
;                     else { const v4u xv = *(const v4u*)(xb + off); x0 = (f32x4){bflo(xv.x), bfhi(xv.x), bflo(xv.y), bfhi(xv.y)}; x1 = (f32x4){bflo(xv.z), bfhi(xv.z), bflo(xv.w), bfhi(xv.w)}; }
	v_lshlrev_b32_e32 v126, 16, v122
	v_and_b32_e32 v127, 0xffff0000, v122
	v_lshlrev_b32_e32 v128, 16, v123
	v_and_b32_e32 v129, 0xffff0000, v123
	v_lshlrev_b32_e32 v122, 16, v124
	v_and_b32_e32 v123, 0xffff0000, v124
	v_lshlrev_b32_e32 v124, 16, v125
	v_and_b32_e32 v125, 0xffff0000, v125
	v_lshlrev_b32_e32 v118, 16, v114
	v_and_b32_e32 v119, 0xffff0000, v114
	v_lshlrev_b32_e32 v120, 16, v115
	v_and_b32_e32 v121, 0xffff0000, v115
	v_lshlrev_b32_e32 v114, 16, v116
	v_and_b32_e32 v115, 0xffff0000, v116
	v_lshlrev_b32_e32 v116, 16, v117
	v_and_b32_e32 v117, 0xffff0000, v117
	v_lshlrev_b32_e32 v110, 16, v106
	v_and_b32_e32 v111, 0xffff0000, v106
	v_lshlrev_b32_e32 v112, 16, v107
	v_and_b32_e32 v113, 0xffff0000, v107
	v_lshlrev_b32_e32 v106, 16, v108
	v_and_b32_e32 v107, 0xffff0000, v108
	v_lshlrev_b32_e32 v108, 16, v109
	v_and_b32_e32 v109, 0xffff0000, v109
	v_lshlrev_b32_e32 v102, 16, v98
	v_and_b32_e32 v103, 0xffff0000, v98
	v_lshlrev_b32_e32 v104, 16, v99
	v_and_b32_e32 v105, 0xffff0000, v99
	v_lshlrev_b32_e32 v98, 16, v100
	v_and_b32_e32 v99, 0xffff0000, v100
	v_lshlrev_b32_e32 v100, 16, v101
	v_and_b32_e32 v101, 0xffff0000, v101
	v_lshlrev_b32_e32 v94, 16, v90
	v_and_b32_e32 v95, 0xffff0000, v90
	v_lshlrev_b32_e32 v96, 16, v91
	v_and_b32_e32 v97, 0xffff0000, v91
	v_lshlrev_b32_e32 v90, 16, v92
	v_and_b32_e32 v91, 0xffff0000, v92
	v_lshlrev_b32_e32 v92, 16, v93
	v_and_b32_e32 v93, 0xffff0000, v93
	v_lshlrev_b32_e32 v86, 16, v82
	v_and_b32_e32 v87, 0xffff0000, v82
	v_lshlrev_b32_e32 v88, 16, v83
	v_and_b32_e32 v89, 0xffff0000, v83
	v_lshlrev_b32_e32 v82, 16, v84
	v_and_b32_e32 v83, 0xffff0000, v84
	v_lshlrev_b32_e32 v84, 16, v85
	v_and_b32_e32 v85, 0xffff0000, v85
	v_lshlrev_b32_e32 v78, 16, v74
	v_and_b32_e32 v79, 0xffff0000, v74
	v_lshlrev_b32_e32 v80, 16, v75
	v_and_b32_e32 v81, 0xffff0000, v75
	v_lshlrev_b32_e32 v74, 16, v76
	v_and_b32_e32 v75, 0xffff0000, v76
	v_lshlrev_b32_e32 v76, 16, v77
	v_and_b32_e32 v77, 0xffff0000, v77
	v_lshlrev_b32_e32 v70, 16, v66
	v_and_b32_e32 v71, 0xffff0000, v66
	v_lshlrev_b32_e32 v72, 16, v67
	v_and_b32_e32 v73, 0xffff0000, v67
	v_lshlrev_b32_e32 v66, 16, v68
	v_and_b32_e32 v67, 0xffff0000, v68
	v_lshlrev_b32_e32 v68, 16, v69
	v_and_b32_e32 v69, 0xffff0000, v69
	v_lshlrev_b32_e32 v62, 16, v58
	v_and_b32_e32 v63, 0xffff0000, v58
	v_lshlrev_b32_e32 v64, 16, v59
	v_and_b32_e32 v65, 0xffff0000, v59
	v_lshlrev_b32_e32 v58, 16, v60
	v_and_b32_e32 v59, 0xffff0000, v60
	v_lshlrev_b32_e32 v60, 16, v61
	v_and_b32_e32 v61, 0xffff0000, v61
	v_lshlrev_b32_e32 v54, 16, v50
	v_and_b32_e32 v55, 0xffff0000, v50
	v_lshlrev_b32_e32 v56, 16, v51
	v_and_b32_e32 v57, 0xffff0000, v51
	v_lshlrev_b32_e32 v50, 16, v52
	v_and_b32_e32 v51, 0xffff0000, v52
	v_lshlrev_b32_e32 v52, 16, v53
	v_and_b32_e32 v53, 0xffff0000, v53
	v_lshlrev_b32_e32 v46, 16, v42
	v_and_b32_e32 v47, 0xffff0000, v42
	v_lshlrev_b32_e32 v48, 16, v43
	v_and_b32_e32 v49, 0xffff0000, v43
	v_lshlrev_b32_e32 v42, 16, v44
	v_and_b32_e32 v43, 0xffff0000, v44
	v_lshlrev_b32_e32 v44, 16, v45
	v_and_b32_e32 v45, 0xffff0000, v45
	v_lshlrev_b32_e32 v38, 16, v34
	v_and_b32_e32 v39, 0xffff0000, v34
	v_lshlrev_b32_e32 v40, 16, v35
	v_and_b32_e32 v41, 0xffff0000, v35
	v_lshlrev_b32_e32 v34, 16, v36
	v_and_b32_e32 v35, 0xffff0000, v36
	v_lshlrev_b32_e32 v36, 16, v37
	v_and_b32_e32 v37, 0xffff0000, v37
	v_lshlrev_b32_e32 v30, 16, v26
	v_and_b32_e32 v31, 0xffff0000, v26
	v_lshlrev_b32_e32 v32, 16, v27
	v_and_b32_e32 v33, 0xffff0000, v27
	v_lshlrev_b32_e32 v26, 16, v28
	v_and_b32_e32 v27, 0xffff0000, v28
	v_lshlrev_b32_e32 v28, 16, v29
	v_and_b32_e32 v29, 0xffff0000, v29
	v_lshlrev_b32_e32 v22, 16, v18
	v_and_b32_e32 v23, 0xffff0000, v18
	v_lshlrev_b32_e32 v24, 16, v19
	v_and_b32_e32 v25, 0xffff0000, v19
	v_lshlrev_b32_e32 v18, 16, v20
	v_and_b32_e32 v19, 0xffff0000, v20
	v_lshlrev_b32_e32 v20, 16, v21
	v_and_b32_e32 v21, 0xffff0000, v21
	v_lshlrev_b32_e32 v14, 16, v10
	v_and_b32_e32 v15, 0xffff0000, v10
	v_lshlrev_b32_e32 v16, 16, v11
	v_and_b32_e32 v17, 0xffff0000, v11
	v_lshlrev_b32_e32 v10, 16, v12
	v_and_b32_e32 v11, 0xffff0000, v12
	v_lshlrev_b32_e32 v12, 16, v13
	v_and_b32_e32 v13, 0xffff0000, v13
	v_lshlrev_b32_e32 v6, 16, v2
	v_and_b32_e32 v7, 0xffff0000, v2
	v_lshlrev_b32_e32 v8, 16, v3
	v_and_b32_e32 v9, 0xffff0000, v3
	v_lshlrev_b32_e32 v2, 16, v4
	v_and_b32_e32 v3, 0xffff0000, v4
	v_lshlrev_b32_e32 v4, 16, v5
	v_and_b32_e32 v5, 0xffff0000, v5

; __device__ __forceinline__ float bflo(unsigned u) { return __uint_as_float(u << 16); }
; __device__ __forceinline__ float bfhi(unsigned u) { return __uint_as_float(u & 0xffff0000u); }
; template <class Epi, class Sched, bool ALIGN_EPI = false, bool SP2 = false>
; __device__ __forceinline__ void gemm_phase(PG8_LAS unsigned char* lds, const Gemm g, const Sched& S, const Epi& E) {
;     ...
; #pragma unroll
;         for (int a = 0; a < 2; ++a)
; #pragma unroll
;             for (int b = 0; b < 2; ++b)
; #pragma unroll
;                 for (int m = 0; m < 4; ++m)
; #pragma unroll
;                     for (int n = 0; n < 2; ++n) acc[a][b][m][n] = (f32x4){0.f, 0.f, 0.f, 0.f};
;         cur = nxt; cA = nA; cB = nB; ++ui;
;     __device__ __forceinline__ void operator()(const f32x4 (&acc)[2][2][4][2], const pg8::Unit& u, int wr, int wc, int fr, int fq) const {
;     ...
;                     const size_t off = (size_t)row * 1024 + c0 + bj * 128;
;                     f32x4 x0, x1;
;                     if (xin) { x0 = *(const f32x4*)(xin + off); x1 = *(const f32x4*)(xin + off + 4); }
;                     else { const v4u xv = *(const v4u*)(xb + off); x0 = (f32x4){bflo(xv.x), bfhi(xv.x), bflo(xv.y), bfhi(xv.y)}; x1 = (f32x4){bflo(xv.z), bfhi(xv.z), bflo(xv.w), bfhi(xv.w)}; }
.LBB0_827:
	s_ashr_i32 s13, s12, 31
	s_lshl_b64 s[14:15], s[12:13], 19
	s_add_u32 s14, s50, s14
	s_addc_u32 s15, s51, s15
	s_and_b64 s[18:19], s[4:5], exec
	s_cselect_b32 s13, s15, s3
	s_cselect_b32 s39, s14, s2
	s_ashr_i32 s11, s10, 31
	s_lshl_b64 s[18:19], s[10:11], 19
	v_readlane_b32 s22, v254, 29
	v_readlane_b32 s23, v254, 30
	s_add_u32 s18, s22, s18
	s_addc_u32 s19, s23, s19
	s_and_b64 s[22:23], s[4:5], exec
	s_cselect_b32 s11, s19, s21
	s_cselect_b32 s40, s18, s20
	s_add_u32 s2, s2, 0x40080
	s_addc_u32 s3, s3, 0
	s_add_u32 s41, s20, 0x100
	v_mov_b32_e32 v2, 0
	s_addc_u32 s42, s21, 0
	s_mov_b32 s43, -2
	s_waitcnt lgkmcnt(0)
	v_mov_b32_e32 v3, v2
	v_mov_b32_e32 v4, v2
	v_mov_b32_e32 v5, v2
	v_mov_b32_e32 v6, v2
	v_mov_b32_e32 v7, v2
	v_mov_b32_e32 v8, v2
	v_mov_b32_e32 v9, v2
	v_mov_b32_e32 v18, v2
	v_mov_b32_e32 v19, v2
	v_mov_b32_e32 v20, v2
	v_mov_b32_e32 v21, v2
	v_mov_b32_e32 v22, v2
	v_mov_b32_e32 v23, v2
	v_mov_b32_e32 v24, v2
	v_mov_b32_e32 v25, v2
	v_mov_b32_e32 v34, v2
	v_mov_b32_e32 v35, v2
	v_mov_b32_e32 v36, v2
	v_mov_b32_e32 v37, v2
	v_mov_b32_e32 v38, v2
	v_mov_b32_e32 v39, v2
	v_mov_b32_e32 v40, v2
	v_mov_b32_e32 v41, v2
	s_waitcnt vmcnt(0)
	v_mov_b32_e32 v50, v2
	v_mov_b32_e32 v51, v2
	v_mov_b32_e32 v52, v2
	v_mov_b32_e32 v53, v2
	v_mov_b32_e32 v54, v2
	v_mov_b32_e32 v55, v2
	v_mov_b32_e32 v56, v2
	v_mov_b32_e32 v57, v2
	v_mov_b32_e32 v10, v2
	v_mov_b32_e32 v11, v2
	v_mov_b32_e32 v12, v2
	v_mov_b32_e32 v13, v2
	v_mov_b32_e32 v14, v2
	v_mov_b32_e32 v15, v2
	v_mov_b32_e32 v16, v2
	v_mov_b32_e32 v17, v2
	v_mov_b32_e32 v26, v2
	v_mov_b32_e32 v27, v2
	v_mov_b32_e32 v28, v2
	v_mov_b32_e32 v29, v2
	v_mov_b32_e32 v30, v2
	v_mov_b32_e32 v31, v2
	v_mov_b32_e32 v32, v2
	v_mov_b32_e32 v33, v2
	v_mov_b32_e32 v42, v2
	v_mov_b32_e32 v43, v2
	v_mov_b32_e32 v44, v2
	v_mov_b32_e32 v45, v2
	v_mov_b32_e32 v46, v2
	v_mov_b32_e32 v47, v2
	v_mov_b32_e32 v48, v2
	v_mov_b32_e32 v49, v2
	v_mov_b32_e32 v58, v2
	v_mov_b32_e32 v59, v2
	v_mov_b32_e32 v60, v2
	v_mov_b32_e32 v61, v2
	v_mov_b32_e32 v62, v2
	v_mov_b32_e32 v63, v2
	v_mov_b32_e32 v64, v2
	v_mov_b32_e32 v65, v2
	v_mov_b32_e32 v66, v2
	v_mov_b32_e32 v67, v2
	v_mov_b32_e32 v68, v2
	v_mov_b32_e32 v69, v2
	v_mov_b32_e32 v70, v2
	v_mov_b32_e32 v71, v2
	v_mov_b32_e32 v72, v2
	v_mov_b32_e32 v73, v2
	v_mov_b32_e32 v82, v2
	v_mov_b32_e32 v83, v2
	v_mov_b32_e32 v84, v2
	v_mov_b32_e32 v85, v2
	v_mov_b32_e32 v86, v2
	v_mov_b32_e32 v87, v2
	v_mov_b32_e32 v88, v2
	v_mov_b32_e32 v89, v2
	v_mov_b32_e32 v98, v2
	v_mov_b32_e32 v99, v2
	v_mov_b32_e32 v100, v2
	v_mov_b32_e32 v101, v2
	v_mov_b32_e32 v102, v2
	v_mov_b32_e32 v103, v2
	v_mov_b32_e32 v104, v2
	v_mov_b32_e32 v105, v2
	v_mov_b32_e32 v114, v2
	v_mov_b32_e32 v115, v2
	v_mov_b32_e32 v116, v2
	v_mov_b32_e32 v117, v2
	v_mov_b32_e32 v118, v2
	v_mov_b32_e32 v119, v2
	v_mov_b32_e32 v120, v2
	v_mov_b32_e32 v121, v2
	v_mov_b32_e32 v74, v2
	v_mov_b32_e32 v75, v2
	v_mov_b32_e32 v76, v2
	v_mov_b32_e32 v77, v2
	v_mov_b32_e32 v78, v2
	v_mov_b32_e32 v79, v2
	v_mov_b32_e32 v80, v2
	v_mov_b32_e32 v81, v2
	v_mov_b32_e32 v90, v2
	v_mov_b32_e32 v91, v2
	v_mov_b32_e32 v92, v2
	v_mov_b32_e32 v93, v2
	v_mov_b32_e32 v94, v2
	v_mov_b32_e32 v95, v2
	v_mov_b32_e32 v96, v2
	v_mov_b32_e32 v97, v2
	v_mov_b32_e32 v106, v2
	v_mov_b32_e32 v107, v2
	v_mov_b32_e32 v108, v2
	v_mov_b32_e32 v109, v2
	v_mov_b32_e32 v110, v2
	v_mov_b32_e32 v111, v2
	v_mov_b32_e32 v112, v2
	v_mov_b32_e32 v113, v2
	v_mov_b32_e32 v122, v2
	v_mov_b32_e32 v123, v2
	v_mov_b32_e32 v124, v2
	v_mov_b32_e32 v125, v2
	v_mov_b32_e32 v126, v2
	v_mov_b32_e32 v127, v2
	v_mov_b32_e32 v128, v2
	v_mov_b32_e32 v129, v2
	v_readlane_b32 s100, v255, 22
	v_readlane_b32 s101, v255, 23
	v_lshl_add_u32 v196, s38, 8, v1
	v_lshl_or_b32 v198, s37, 8, v170
	v_ashrrev_i32_e32 v197, 31, v196
	v_ashrrev_i32_e32 v199, 31, v198
	v_lshlrev_b64 v[200:201], 10, v[196:197]
	v_lshl_add_u64 v[200:201], v[200:201], 0, v[198:199]
	v_lshl_add_u64 v[200:201], v[200:201], 1, s[100:101]
	v_mov_b32_e32 v217, 0
	v_mov_b32_e32 v216, 0x8000
	v_lshl_add_u64 v[202:203], v[200:201], 0, v[216:217]
	v_mov_b32_e32 v216, 0x10000
	v_lshl_add_u64 v[204:205], v[200:201], 0, v[216:217]
	v_mov_b32_e32 v216, 0x18000
	v_lshl_add_u64 v[206:207], v[200:201], 0, v[216:217]
	v_mov_b32_e32 v216, 0x40000
	v_lshl_add_u64 v[208:209], v[200:201], 0, v[216:217]
	v_mov_b32_e32 v216, 0x48000
	v_lshl_add_u64 v[210:211], v[200:201], 0, v[216:217]
	v_mov_b32_e32 v216, 0x50000
	v_lshl_add_u64 v[212:213], v[200:201], 0, v[216:217]
	v_mov_b32_e32 v216, 0x58000
	v_lshl_add_u64 v[214:215], v[200:201], 0, v[216:217]
	global_load_dwordx4 v[122:125], v[200:201], off nt
	global_load_dwordx4 v[114:117], v[200:201], off offset:256 nt
	global_load_dwordx4 v[106:109], v[202:203], off nt
	global_load_dwordx4 v[98:101], v[202:203], off offset:256 nt
	global_load_dwordx4 v[90:93], v[204:205], off nt
	global_load_dwordx4 v[82:85], v[204:205], off offset:256 nt
	global_load_dwordx4 v[74:77], v[206:207], off nt
	global_load_dwordx4 v[66:69], v[206:207], off offset:256 nt
	global_load_dwordx4 v[58:61], v[208:209], off nt
	global_load_dwordx4 v[50:53], v[208:209], off offset:256 nt
	global_load_dwordx4 v[42:45], v[210:211], off nt
	global_load_dwordx4 v[34:37], v[210:211], off offset:256 nt
	global_load_dwordx4 v[26:29], v[212:213], off nt
	global_load_dwordx4 v[18:21], v[212:213], off offset:256 nt
	global_load_dwordx4 v[10:13], v[214:215], off nt
	global_load_dwordx4 v[2:5], v[214:215], off offset:256 nt
	s_waitcnt vmcnt(0)
; __device__ __forceinline__ float bflo(unsigned u) { return __uint_as_float(u << 16); }
; __device__ __forceinline__ float bfhi(unsigned u) { return __uint_as_float(u & 0xffff0000u); }
;     __device__ __forceinline__ void operator()(const f32x4 (&acc)[2][2][4][2], const pg8::Unit& u, int wr, int wc, int fr, int fq) const {
;     ...
;                     else { const v4u xv = *(const v4u*)(xb + off); x0 = (f32x4){bflo(xv.x), bfhi(xv.x), bflo(xv.y), bfhi(xv.y)}; x1 = (f32x4){bflo(xv.z), bfhi(xv.z), bflo(xv.w), bfhi(xv.w)}; }
	v_lshlrev_b32_e32 v126, 16, v122
	v_and_b32_e32 v127, 0xffff0000, v122
	v_lshlrev_b32_e32 v128, 16, v123
	v_and_b32_e32 v129, 0xffff0000, v123
	v_lshlrev_b32_e32 v122, 16, v124
	v_and_b32_e32 v123, 0xffff0000, v124
	v_lshlrev_b32_e32 v124, 16, v125
	v_and_b32_e32 v125, 0xffff0000, v125
	v_lshlrev_b32_e32 v118, 16, v114
	v_and_b32_e32 v119, 0xffff0000, v114
	v_lshlrev_b32_e32 v120, 16, v115
	v_and_b32_e32 v121, 0xffff0000, v115
	v_lshlrev_b32_e32 v114, 16, v116
	v_and_b32_e32 v115, 0xffff0000, v116
	v_lshlrev_b32_e32 v116, 16, v117
	v_and_b32_e32 v117, 0xffff0000, v117
	v_lshlrev_b32_e32 v110, 16, v106
	v_and_b32_e32 v111, 0xffff0000, v106
	v_lshlrev_b32_e32 v112, 16, v107
	v_and_b32_e32 v113, 0xffff0000, v107
	v_lshlrev_b32_e32 v106, 16, v108
	v_and_b32_e32 v107, 0xffff0000, v108
	v_lshlrev_b32_e32 v108, 16, v109
	v_and_b32_e32 v109, 0xffff0000, v109
	v_lshlrev_b32_e32 v102, 16, v98
	v_and_b32_e32 v103, 0xffff0000, v98
	v_lshlrev_b32_e32 v104, 16, v99
	v_and_b32_e32 v105, 0xffff0000, v99
	v_lshlrev_b32_e32 v98, 16, v100
	v_and_b32_e32 v99, 0xffff0000, v100
	v_lshlrev_b32_e32 v100, 16, v101
	v_and_b32_e32 v101, 0xffff0000, v101
	v_lshlrev_b32_e32 v94, 16, v90
	v_and_b32_e32 v95, 0xffff0000, v90
	v_lshlrev_b32_e32 v96, 16, v91
	v_and_b32_e32 v97, 0xffff0000, v91
	v_lshlrev_b32_e32 v90, 16, v92
	v_and_b32_e32 v91, 0xffff0000, v92
	v_lshlrev_b32_e32 v92, 16, v93
	v_and_b32_e32 v93, 0xffff0000, v93
	v_lshlrev_b32_e32 v86, 16, v82
	v_and_b32_e32 v87, 0xffff0000, v82
	v_lshlrev_b32_e32 v88, 16, v83
	v_and_b32_e32 v89, 0xffff0000, v83
	v_lshlrev_b32_e32 v82, 16, v84
	v_and_b32_e32 v83, 0xffff0000, v84
	v_lshlrev_b32_e32 v84, 16, v85
	v_and_b32_e32 v85, 0xffff0000, v85
	v_lshlrev_b32_e32 v78, 16, v74
	v_and_b32_e32 v79, 0xffff0000, v74
	v_lshlrev_b32_e32 v80, 16, v75
	v_and_b32_e32 v81, 0xffff0000, v75
	v_lshlrev_b32_e32 v74, 16, v76
	v_and_b32_e32 v75, 0xffff0000, v76
	v_lshlrev_b32_e32 v76, 16, v77
	v_and_b32_e32 v77, 0xffff0000, v77
	v_lshlrev_b32_e32 v70, 16, v66
	v_and_b32_e32 v71, 0xffff0000, v66
	v_lshlrev_b32_e32 v72, 16, v67
	v_and_b32_e32 v73, 0xffff0000, v67
	v_lshlrev_b32_e32 v66, 16, v68
	v_and_b32_e32 v67, 0xffff0000, v68
	v_lshlrev_b32_e32 v68, 16, v69
	v_and_b32_e32 v69, 0xffff0000, v69
	v_lshlrev_b32_e32 v62, 16, v58
	v_and_b32_e32 v63, 0xffff0000, v58
	v_lshlrev_b32_e32 v64, 16, v59
	v_and_b32_e32 v65, 0xffff0000, v59
	v_lshlrev_b32_e32 v58, 16, v60
	v_and_b32_e32 v59, 0xffff0000, v60
	v_lshlrev_b32_e32 v60, 16, v61
	v_and_b32_e32 v61, 0xffff0000, v61
	v_lshlrev_b32_e32 v54, 16, v50
	v_and_b32_e32 v55, 0xffff0000, v50
	v_lshlrev_b32_e32 v56, 16, v51
	v_and_b32_e32 v57, 0xffff0000, v51
	v_lshlrev_b32_e32 v50, 16, v52
	v_and_b32_e32 v51, 0xffff0000, v52
	v_lshlrev_b32_e32 v52, 16, v53
	v_and_b32_e32 v53, 0xffff0000, v53
	v_lshlrev_b32_e32 v46, 16, v42
	v_and_b32_e32 v47, 0xffff0000, v42
	v_lshlrev_b32_e32 v48, 16, v43
	v_and_b32_e32 v49, 0xffff0000, v43
	v_lshlrev_b32_e32 v42, 16, v44
	v_and_b32_e32 v43, 0xffff0000, v44
	v_lshlrev_b32_e32 v44, 16, v45
	v_and_b32_e32 v45, 0xffff0000, v45
	v_lshlrev_b32_e32 v38, 16, v34
	v_and_b32_e32 v39, 0xffff0000, v34
	v_lshlrev_b32_e32 v40, 16, v35
	v_and_b32_e32 v41, 0xffff0000, v35
	v_lshlrev_b32_e32 v34, 16, v36
	v_and_b32_e32 v35, 0xffff0000, v36
	v_lshlrev_b32_e32 v36, 16, v37
	v_and_b32_e32 v37, 0xffff0000, v37
	v_lshlrev_b32_e32 v30, 16, v26
	v_and_b32_e32 v31, 0xffff0000, v26
	v_lshlrev_b32_e32 v32, 16, v27
	v_and_b32_e32 v33, 0xffff0000, v27
	v_lshlrev_b32_e32 v26, 16, v28
	v_and_b32_e32 v27, 0xffff0000, v28
	v_lshlrev_b32_e32 v28, 16, v29
	v_and_b32_e32 v29, 0xffff0000, v29
	v_lshlrev_b32_e32 v22, 16, v18
	v_and_b32_e32 v23, 0xffff0000, v18
	v_lshlrev_b32_e32 v24, 16, v19
	v_and_b32_e32 v25, 0xffff0000, v19
	v_lshlrev_b32_e32 v18, 16, v20
	v_and_b32_e32 v19, 0xffff0000, v20
	v_lshlrev_b32_e32 v20, 16, v21
	v_and_b32_e32 v21, 0xffff0000, v21
	v_lshlrev_b32_e32 v14, 16, v10
	v_and_b32_e32 v15, 0xffff0000, v10
	v_lshlrev_b32_e32 v16, 16, v11
	v_and_b32_e32 v17, 0xffff0000, v11
	v_lshlrev_b32_e32 v10, 16, v12
	v_and_b32_e32 v11, 0xffff0000, v12
	v_lshlrev_b32_e32 v12, 16, v13
	v_and_b32_e32 v13, 0xffff0000, v13
	v_lshlrev_b32_e32 v6, 16, v2
	v_and_b32_e32 v7, 0xffff0000, v2
	v_lshlrev_b32_e32 v8, 16, v3
	v_and_b32_e32 v9, 0xffff0000, v3
	v_lshlrev_b32_e32 v2, 16, v4
	v_and_b32_e32 v3, 0xffff0000, v4
	v_lshlrev_b32_e32 v4, 16, v5
	v_and_b32_e32 v5, 0xffff0000, v5
